# row phase (k=2 instance) prologue: 20 modulation/gain vector loads issued back-to-back into fresh registers, scaling after one counted wait
# baseline (speedup 1.0000x reference)
.LBB0_1082:
	s_andn2_b64 vcc, exec, s[2:3]
	s_cbranch_vccnz .LBB0_1096
	s_cmp_gt_i32 s71, 1
	s_mov_b64 s[2:3], -1
	s_cbranch_scc0 .LBB0_1094
	s_waitcnt vmcnt(0)
	v_mov_b32_e32 v48, v135
	s_mov_b64 s[2:3], s[0:1]
	s_mov_b64 s[2:3], s[0:1]
	s_mov_b64 s[4:5], s[0:1]
	s_mov_b64 s[6:7], s[0:1]
	s_mov_b64 s[6:7], s[0:1]
	s_lshl_b32 s6, s19, 3
	s_abs_i32 s6, s6
	v_cvt_f32_u32_e32 v0, s6
	s_sub_i32 s8, 0, s6
	s_bfe_i32 s7, s19, 0x1001c
	v_rcp_iflag_f32_e32 v0, v0
	s_nop 0
	v_mul_f32_e32 v0, 0x4f7ffffe, v0
	v_cvt_u32_f32_e32 v0, v0
	s_nop 0
	v_readfirstlane_b32 s9, v0
	s_mul_i32 s8, s8, s9
	s_mul_hi_u32 s8, s9, s8
	s_add_i32 s9, s9, s8
	s_lshr_b32 s8, s9, 18
	s_mul_i32 s9, s8, s6
	s_sub_i32 s9, 0x4000, s9
	s_add_i32 s10, s8, 1
	s_sub_i32 s11, s9, s6
	s_cmp_ge_u32 s9, s6
	s_cselect_b32 s8, s10, s8
	s_cselect_b32 s9, s11, s9
	s_add_i32 s10, s8, 1
	s_cmp_ge_u32 s9, s6
	s_cselect_b32 s6, s10, s8
	s_xor_b32 s6, s6, s7
	s_sub_i32 s8, s6, s7
	s_cmp_lt_i32 s8, 1
	s_cbranch_scc1 .LBB0_1087
	v_ashrrev_i32_e32 v0, 6, v48
	v_readlane_b32 s6, v254, 3
	s_load_dwordx2 s[2:3], s[2:3], 0x88
	s_nop 0
	s_load_dwordx2 s[4:5], s[4:5], 0x40
	v_add_u32_e32 v0, s6, v0
	v_mul_lo_u32 v56, s8, v0
	v_add_u32_e32 v0, 0xffffe000, v56
	v_ashrrev_i32_e32 v0, 11, v0
	s_movk_i32 s6, 0x1fff
	v_add_u32_e32 v0, 1, v0
	v_cmp_lt_i32_e32 vcc, s6, v56
	s_waitcnt lgkmcnt(0)
	v_mov_b64_e32 v[2:3], s[2:3]
	v_mov_b32_e32 v41, v133
	v_cndmask_b32_e32 v0, 0, v0, vcc
	v_mad_u64_u32 v[0:1], s[6:7], s40, 5, v[0:1]
	v_mad_i64_i32 v[20:21], s[6:7], v0, s90, v[2:3]
	v_lshlrev_b32_e32 v0, 3, v48
	s_mov_b64 s[6:7], 0x6242000
	v_and_b32_e32 v49, 0x1f8, v0
	v_lshl_add_u64 v[12:13], v[20:21], 0, s[6:7]
	v_lshlrev_b32_e32 v132, 2, v49
	v_lshl_add_u64 v[0:1], v[12:13], 0, v[132:133]
	global_load_dwordx4 v[216:219], v[0:1], off offset:16
	s_nop 0
	global_load_dwordx4 v[220:223], v[0:1], off
	s_mul_i32 s6, s40, 0x1800
	s_ashr_i32 s7, s6, 31
	s_lshl_b64 s[10:11], s[6:7], 2
	s_add_u32 s7, s4, s10
	s_addc_u32 s9, s5, s11
	s_add_u32 s10, s7, 0x1000
	v_or_b32_e32 v40, 0x800, v132
	s_addc_u32 s11, s9, 0
	s_add_i32 s58, s6, 0x800
	s_lshl_b64 s[6:7], s[58:59], 2
	s_add_u32 s4, s4, s6
	s_addc_u32 s5, s5, s7
	v_ashrrev_i32_e32 v57, 31, v56
	v_and_b32_e32 v48, 63, v48
	v_lshl_add_u64 v[8:9], v[12:13], 0, v[40:41]
	global_load_dwordx4 v[0:3], v132, s[10:11] offset:16
	global_load_dwordx4 v[4:7], v132, s[10:11]
	global_load_dwordx4 v[224:227], v[8:9], off offset:16
	s_nop 0
	global_load_dwordx4 v[228:231], v[8:9], off
	global_load_dwordx4 v[8:11], v40, s[10:11] offset:16
	global_load_dwordx4 v[12:15], v40, s[10:11]
	s_mov_b64 s[10:11], 0x6243000
	v_lshl_add_u64 v[36:37], v[20:21], 0, s[10:11]
	s_mov_b64 s[10:11], 0x6244000
	v_lshl_add_u64 v[42:43], v[20:21], 0, s[10:11]
	v_lshl_add_u64 v[20:21], v[36:37], 0, v[132:133]
	v_lshl_add_u64 v[24:25], v[42:43], 0, v[132:133]
	global_load_dwordx4 v[16:19], v[20:21], off offset:16
	s_nop 0
	global_load_dwordx4 v[20:23], v[20:21], off
	s_nop 0
	global_load_dwordx4 v[232:235], v[24:25], off offset:16
	s_nop 0
	global_load_dwordx4 v[236:239], v[24:25], off
	v_lshl_add_u64 v[36:37], v[36:37], 0, v[40:41]
	v_lshl_add_u64 v[40:41], v[42:43], 0, v[40:41]
	global_load_dwordx4 v[24:27], v132, s[4:5] offset:16
	global_load_dwordx4 v[28:31], v132, s[4:5]
	global_load_dwordx4 v[32:35], v[36:37], off offset:16
	s_nop 0
	global_load_dwordx4 v[36:39], v[36:37], off
	s_nop 0
	global_load_dwordx4 v[240:243], v[40:41], off offset:16
	s_nop 0
	global_load_dwordx4 v[244:247], v[40:41], off
	global_load_dwordx4 v[40:43], v132, s[4:5] offset:2064
	global_load_dwordx4 v[44:47], v132, s[4:5] offset:2048
	s_add_u32 s4, s2, 0x62a4400
	v_lshlrev_b32_e32 v132, 1, v49
	s_addc_u32 s5, s3, 0
	v_lshl_add_u64 v[50:51], s[2:3], 0, v[132:133]
	s_mov_b64 s[2:3], 0x82a4400
	v_lshl_add_u64 v[90:91], v[50:51], 0, s[2:3]
	v_lshlrev_b64 v[50:51], 11, v[56:57]
	v_lshl_or_b32 v50, v48, 4, v50
	v_lshl_add_u64 v[92:93], s[4:5], 0, v[132:133]
	v_lshl_add_u64 v[94:95], s[4:5], 0, v[50:51]
	s_mov_b64 s[2:3], 0
	s_waitcnt vmcnt(2)
	v_pk_mul_f32 v[64:65], v[216:217], 0.5 op_sel_hi:[1,0]
	v_pk_mul_f32 v[58:59], v[222:223], 0.5 op_sel_hi:[1,0]
	v_pk_mul_f32 v[60:61], v[220:221], 0.5 op_sel_hi:[1,0]
	v_pk_mul_f32 v[62:63], v[218:219], 0.5 op_sel_hi:[1,0]
	v_pk_mul_f32 v[70:71], v[226:227], 0.5 op_sel_hi:[1,0]
	v_pk_mul_f32 v[66:67], v[230:231], 0.5 op_sel_hi:[1,0]
	v_pk_mul_f32 v[68:69], v[228:229], 0.5 op_sel_hi:[1,0]
	v_pk_mul_f32 v[72:73], v[224:225], 0.5 op_sel_hi:[1,0]
	v_pk_add_f32 v[78:79], v[234:235], 1.0 op_sel_hi:[1,0]
	v_pk_add_f32 v[74:75], v[238:239], 1.0 op_sel_hi:[1,0]
	v_pk_add_f32 v[76:77], v[236:237], 1.0 op_sel_hi:[1,0]
	v_pk_add_f32 v[80:81], v[232:233], 1.0 op_sel_hi:[1,0]
	v_pk_add_f32 v[88:89], v[240:241], 1.0 op_sel_hi:[1,0]
	v_pk_add_f32 v[82:83], v[246:247], 1.0 op_sel_hi:[1,0]
	v_pk_add_f32 v[84:85], v[244:245], 1.0 op_sel_hi:[1,0]
	v_pk_add_f32 v[86:87], v[242:243], 1.0 op_sel_hi:[1,0]
